# speedup vs baseline: 1.0105x; 1.0105x over previous
; __device__ __forceinline__ unsigned cvt_pk_bf16(float lo, float hi) { unsigned r; asm volatile("v_cvt_pk_bf16_f32 %0, %1, %2" : "=v"(r) : "v"(lo), "v"(hi)); return r; }
;     __device__ __forceinline__ void operator()(const f32x4 (&acc)[2][2][4][2], const Unit& u, int wr, int wc, int fr, int fq) const {
;         const int row0 = u.pm * BM + wr * 64 + fr, col0 = u.pn * BM + wc * 32 + 4 * fq;
;         const bool addres = u.ks <= 0;
;         bf16_t* base = u.ks >= 0 ? YP + ((size_t)u.ks * MS - (size_t)MP) * DM : Y;
; #pragma unroll
;         for (int ai = 0; ai < 2; ++ai)
; #pragma unroll
;             for (int m = 0; m < 4; ++m) { const size_t off = (size_t)(row0 + ai * HALF + m * 16) * DM + col0, roff = (size_t)(row0 + ai * HALF + m * 16) * LDX + col0;
; #pragma unroll
;                 for (int bj = 0; bj < 2; ++bj)
; #pragma unroll
;                     for (int n = 0; n < 2; ++n) { f32x4 o = acc[ai][bj][m][n];
;                         if (addres) { const u32x2 w = *(const u32x2*)(res + roff + bj * HALF + n * 16);
;                             o[0] += ALPHA * __uint_as_float(w.x << 16); o[1] += ALPHA * __uint_as_float(w.x & 0xffff0000u); o[2] += ALPHA * __uint_as_float(w.y << 16); o[3] += ALPHA * __uint_as_float(w.y & 0xffff0000u); }
;                         u32x2 pk; pk.x = cvt_pk_bf16(o[0], o[1]); pk.y = cvt_pk_bf16(o[2], o[3]);
;                         *(u32x2*)(base + off + bj * HALF + n * 16) = pk; } }
.LBB0_482:
	s_cmp_lt_i32 s0, 0
	v_readlane_b32 s2, v250, 34
	s_cselect_b64 s[12:13], -1, 0
	v_readlane_b32 s3, v250, 35
	s_and_b64 s[6:7], s[2:3], s[12:13]
	s_mov_b64 s[2:3], -1
	s_andn2_b64 vcc, exec, s[6:7]
	v_lshl_or_b32 v134, s46, 8, v228
	v_readlane_b32 s35, v251, 41
	s_mov_b64 s[14:15], s[80:81]
	s_mov_b32 s44, s27
	s_cbranch_vccz .LBB0_548
	s_cmp_lt_i32 s0, 1
	v_lshl_add_u32 v136, s88, 8, v219
	s_cselect_b64 s[10:11], -1, 0
	s_cmp_gt_i32 s0, 0
	v_ashrrev_i32_e32 v135, 31, v134
	v_mad_i64_i32 v[140:141], s[2:3], v136, s93, 0
	v_mov_b32_e32 v144, v118
	v_mov_b32_e32 v145, v119
	v_mov_b32_e32 v146, v120
	v_mov_b32_e32 v147, v121
	s_cbranch_scc1 .LBB0_485
	v_mad_i64_i32 v[198:199], s[2:3], v136, s93, 0
	v_lshl_add_u64 v[198:199], s[28:29], 0, v[198:199]
	v_lshl_add_u64 v[198:199], v[134:135], 1, v[198:199]
	global_load_dwordx2 v[150:151], v[198:199], off
	global_load_dwordx2 v[152:153], v[198:199], off offset:32
	global_load_dwordx2 v[154:155], v[198:199], off offset:256
	global_load_dwordx2 v[156:157], v[198:199], off offset:288
	v_add_u32_e32 v198, 0x10, v136
	v_mad_i64_i32 v[198:199], s[2:3], v198, s93, 0
	v_lshl_add_u64 v[198:199], s[28:29], 0, v[198:199]
	v_lshl_add_u64 v[198:199], v[134:135], 1, v[198:199]
	global_load_dwordx2 v[158:159], v[198:199], off
	global_load_dwordx2 v[160:161], v[198:199], off offset:32
	global_load_dwordx2 v[162:163], v[198:199], off offset:256
	global_load_dwordx2 v[164:165], v[198:199], off offset:288
	v_add_u32_e32 v198, 0x20, v136
	v_mad_i64_i32 v[198:199], s[2:3], v198, s93, 0
	v_lshl_add_u64 v[198:199], s[28:29], 0, v[198:199]
	v_lshl_add_u64 v[198:199], v[134:135], 1, v[198:199]
	global_load_dwordx2 v[166:167], v[198:199], off
	global_load_dwordx2 v[168:169], v[198:199], off offset:32
	global_load_dwordx2 v[170:171], v[198:199], off offset:256
	global_load_dwordx2 v[172:173], v[198:199], off offset:288
	v_add_u32_e32 v198, 0x30, v136
	v_mad_i64_i32 v[198:199], s[2:3], v198, s93, 0
	v_lshl_add_u64 v[198:199], s[28:29], 0, v[198:199]
	v_lshl_add_u64 v[198:199], v[134:135], 1, v[198:199]
	global_load_dwordx2 v[174:175], v[198:199], off
	global_load_dwordx2 v[176:177], v[198:199], off offset:32
	global_load_dwordx2 v[178:179], v[198:199], off offset:256
	global_load_dwordx2 v[180:181], v[198:199], off offset:288
	v_add_u32_e32 v198, 0x80, v136
	v_mad_i64_i32 v[198:199], s[2:3], v198, s93, 0
	v_lshl_add_u64 v[198:199], s[28:29], 0, v[198:199]
	v_lshl_add_u64 v[198:199], v[134:135], 1, v[198:199]
	global_load_dwordx2 v[182:183], v[198:199], off
	global_load_dwordx2 v[184:185], v[198:199], off offset:32
	global_load_dwordx2 v[186:187], v[198:199], off offset:256
	global_load_dwordx2 v[188:189], v[198:199], off offset:288
	v_add_u32_e32 v198, 0x90, v136
	v_mad_i64_i32 v[198:199], s[2:3], v198, s93, 0
	v_lshl_add_u64 v[198:199], s[28:29], 0, v[198:199]
	v_lshl_add_u64 v[198:199], v[134:135], 1, v[198:199]
	global_load_dwordx2 v[190:191], v[198:199], off
	global_load_dwordx2 v[192:193], v[198:199], off offset:32
	global_load_dwordx2 v[194:195], v[198:199], off offset:256
	global_load_dwordx2 v[196:197], v[198:199], off offset:288
	s_waitcnt vmcnt(23)
	v_lshlrev_b32_e32 v142, 16, v150
	v_and_b32_e32 v143, 0xffff0000, v150
	v_lshlrev_b32_e32 v138, 16, v151
	v_and_b32_e32 v139, 0xffff0000, v151
	v_add_u32_e32 v198, 0xa0, v136
	v_mad_i64_i32 v[198:199], s[2:3], v198, s93, 0
	v_lshl_add_u64 v[198:199], s[28:29], 0, v[198:199]
	v_lshl_add_u64 v[198:199], v[134:135], 1, v[198:199]
	global_load_dwordx2 v[150:151], v[198:199], off
	v_pk_fma_f32 v[144:145], v[142:143], s[30:31], v[118:119] op_sel_hi:[1,0,1]
	v_pk_fma_f32 v[146:147], v[138:139], s[30:31], v[120:121] op_sel_hi:[1,0,1]
.LBB0_485:
	s_mov_b32 s1, s95
	s_lshl_b64 s[0:1], s[0:1], 22
	v_readlane_b32 s2, v250, 36
	v_readlane_b32 s3, v250, 37
	s_add_u32 s0, s2, s0
	s_addc_u32 s1, s3, s1
	s_add_u32 s2, s0, 0xfe000000
	s_addc_u32 s3, s1, -1
	v_readlane_b32 s6, v249, 9
	s_and_b64 s[0:1], s[12:13], exec
	v_readlane_b32 s7, v249, 10
	s_cselect_b32 s0, s7, s3
	s_cselect_b32 s1, s6, s2
	v_ashrrev_i32_e32 v137, 31, v136
	v_mov_b32_e32 v138, s1
	v_mov_b32_e32 v139, s0
	v_lshl_add_u64 v[138:139], v[134:135], 1, v[138:139]
	v_lshlrev_b64 v[142:143], 12, v[136:137]
	v_lshl_add_u64 v[142:143], v[138:139], 0, v[142:143]
	v_cvt_pk_bf16_f32 v144, v144, v145
	v_cvt_pk_bf16_f32 v145, v146, v147
	v_cndmask_b32_e64 v64, 0, 1, s[10:11]
	global_store_dwordx2 v[142:143], v[144:145], off
	v_cmp_ne_u32_e64 s[0:1], 1, v64
	s_andn2_b64 vcc, exec, s[10:11]
	v_mov_b32_e32 v144, v114
	v_mov_b32_e32 v145, v115
	v_mov_b32_e32 v146, v116
	v_mov_b32_e32 v147, v117
	s_cbranch_vccnz .LBB0_487
	s_waitcnt vmcnt(24)
	v_lshlrev_b32_e32 v146, 16, v152
	v_and_b32_e32 v147, 0xffff0000, v152
	v_lshlrev_b32_e32 v148, 16, v153
	v_and_b32_e32 v149, 0xffff0000, v153
	v_add_u32_e32 v198, 0xa0, v136
	v_mad_i64_i32 v[198:199], s[2:3], v198, s93, 0
	v_lshl_add_u64 v[198:199], s[28:29], 0, v[198:199]
	v_lshl_add_u64 v[198:199], v[134:135], 1, v[198:199]
	global_load_dwordx2 v[152:153], v[198:199], off offset:32
	v_pk_fma_f32 v[144:145], v[146:147], s[30:31], v[114:115] op_sel_hi:[1,0,1]
	v_pk_fma_f32 v[146:147], v[148:149], s[30:31], v[116:117] op_sel_hi:[1,0,1]
.LBB0_487:
	v_cvt_pk_bf16_f32 v144, v144, v145
	s_nop 0
	v_cvt_pk_bf16_f32 v145, v146, v147
	global_store_dwordx2 v[142:143], v[144:145], off offset:32
	s_and_b64 vcc, exec, s[0:1]
	v_mov_b32_e32 v144, v126
	v_mov_b32_e32 v145, v127
	v_mov_b32_e32 v146, v128
	v_mov_b32_e32 v147, v129
	s_cbranch_vccnz .LBB0_489
	s_waitcnt vmcnt(25)
	v_lshlrev_b32_e32 v146, 16, v154
	v_and_b32_e32 v147, 0xffff0000, v154
	v_lshlrev_b32_e32 v148, 16, v155
	v_and_b32_e32 v149, 0xffff0000, v155
	v_add_u32_e32 v198, 0xa0, v136
	v_mad_i64_i32 v[198:199], s[2:3], v198, s93, 0
	v_lshl_add_u64 v[198:199], s[28:29], 0, v[198:199]
	v_lshl_add_u64 v[198:199], v[134:135], 1, v[198:199]
	global_load_dwordx2 v[154:155], v[198:199], off offset:256
	v_pk_fma_f32 v[144:145], v[146:147], s[30:31], v[126:127] op_sel_hi:[1,0,1]
	v_pk_fma_f32 v[146:147], v[148:149], s[30:31], v[128:129] op_sel_hi:[1,0,1]
; __device__ __forceinline__ unsigned cvt_pk_bf16(float lo, float hi) { unsigned r; asm volatile("v_cvt_pk_bf16_f32 %0, %1, %2" : "=v"(r) : "v"(lo), "v"(hi)); return r; }
;     __device__ __forceinline__ void operator()(const f32x4 (&acc)[2][2][4][2], const Unit& u, int wr, int wc, int fr, int fq) const {
;     ...
;             for (int m = 0; m < 4; ++m) { const size_t off = (size_t)(row0 + ai * HALF + m * 16) * DM + col0, roff = (size_t)(row0 + ai * HALF + m * 16) * LDX + col0;
; #pragma unroll
;                 for (int bj = 0; bj < 2; ++bj)
; #pragma unroll
;                     for (int n = 0; n < 2; ++n) { f32x4 o = acc[ai][bj][m][n];
;                         if (addres) { const u32x2 w = *(const u32x2*)(res + roff + bj * HALF + n * 16);
;                             o[0] += ALPHA * __uint_as_float(w.x << 16); o[1] += ALPHA * __uint_as_float(w.x & 0xffff0000u); o[2] += ALPHA * __uint_as_float(w.y << 16); o[3] += ALPHA * __uint_as_float(w.y & 0xffff0000u); }
;                         u32x2 pk; pk.x = cvt_pk_bf16(o[0], o[1]); pk.y = cvt_pk_bf16(o[2], o[3]);
;                         *(u32x2*)(base + off + bj * HALF + n * 16) = pk; } }
.LBB0_489:
	v_cvt_pk_bf16_f32 v144, v144, v145
	s_nop 0
	v_cvt_pk_bf16_f32 v145, v146, v147
	global_store_dwordx2 v[142:143], v[144:145], off offset:256
	s_and_b64 vcc, exec, s[0:1]
	v_mov_b32_e32 v144, v122
	v_mov_b32_e32 v145, v123
	v_mov_b32_e32 v146, v124
	v_mov_b32_e32 v147, v125
	s_cbranch_vccnz .LBB0_491
	s_waitcnt vmcnt(26)
	v_lshlrev_b32_e32 v144, 16, v156
	v_and_b32_e32 v145, 0xffff0000, v156
	v_lshlrev_b32_e32 v140, 16, v157
	v_and_b32_e32 v141, 0xffff0000, v157
	v_add_u32_e32 v198, 0xa0, v136
	v_mad_i64_i32 v[198:199], s[2:3], v198, s93, 0
	v_lshl_add_u64 v[198:199], s[28:29], 0, v[198:199]
	v_lshl_add_u64 v[198:199], v[134:135], 1, v[198:199]
	global_load_dwordx2 v[156:157], v[198:199], off offset:288
	v_pk_fma_f32 v[144:145], v[144:145], s[30:31], v[122:123] op_sel_hi:[1,0,1]
	v_pk_fma_f32 v[146:147], v[140:141], s[30:31], v[124:125] op_sel_hi:[1,0,1]
.LBB0_491:
	v_cvt_pk_bf16_f32 v140, v144, v145
	s_nop 0
	v_cvt_pk_bf16_f32 v141, v146, v147
	global_store_dwordx2 v[142:143], v[140:141], off offset:288
	v_or_b32_e32 v142, 16, v136
	v_mad_i64_i32 v[140:141], s[2:3], v142, s93, 0
	s_and_b64 vcc, exec, s[0:1]
	v_mov_b32_e32 v144, v102
	v_mov_b32_e32 v145, v103
	v_mov_b32_e32 v146, v104
	v_mov_b32_e32 v147, v105
	s_cbranch_vccnz .LBB0_493
	s_waitcnt vmcnt(27)
	v_lshlrev_b32_e32 v146, 16, v158
	v_and_b32_e32 v147, 0xffff0000, v158
	v_lshlrev_b32_e32 v148, 16, v159
	v_and_b32_e32 v149, 0xffff0000, v159
	v_add_u32_e32 v198, 0xb0, v136
	v_mad_i64_i32 v[198:199], s[2:3], v198, s93, 0
	v_lshl_add_u64 v[198:199], s[28:29], 0, v[198:199]
	v_lshl_add_u64 v[198:199], v[134:135], 1, v[198:199]
	global_load_dwordx2 v[158:159], v[198:199], off
	v_pk_fma_f32 v[144:145], v[146:147], s[30:31], v[102:103] op_sel_hi:[1,0,1]
	v_pk_fma_f32 v[146:147], v[148:149], s[30:31], v[104:105] op_sel_hi:[1,0,1]
.LBB0_493:
	v_ashrrev_i32_e32 v143, 31, v142
	v_lshlrev_b64 v[142:143], 12, v[142:143]
	v_lshl_add_u64 v[142:143], v[138:139], 0, v[142:143]
	v_cvt_pk_bf16_f32 v144, v144, v145
	v_cvt_pk_bf16_f32 v145, v146, v147
	global_store_dwordx2 v[142:143], v[144:145], off
	s_and_b64 vcc, exec, s[0:1]
	v_mov_b32_e32 v144, v98
	v_mov_b32_e32 v145, v99
	v_mov_b32_e32 v146, v100
	v_mov_b32_e32 v147, v101
	s_cbranch_vccnz .LBB0_495
	s_waitcnt vmcnt(28)
	v_lshlrev_b32_e32 v146, 16, v160
	v_and_b32_e32 v147, 0xffff0000, v160
	v_lshlrev_b32_e32 v148, 16, v161
	v_and_b32_e32 v149, 0xffff0000, v161
	v_add_u32_e32 v198, 0xb0, v136
	v_mad_i64_i32 v[198:199], s[2:3], v198, s93, 0
	v_lshl_add_u64 v[198:199], s[28:29], 0, v[198:199]
	v_lshl_add_u64 v[198:199], v[134:135], 1, v[198:199]
	global_load_dwordx2 v[160:161], v[198:199], off offset:32
	v_pk_fma_f32 v[144:145], v[146:147], s[30:31], v[98:99] op_sel_hi:[1,0,1]
	v_pk_fma_f32 v[146:147], v[148:149], s[30:31], v[100:101] op_sel_hi:[1,0,1]
.LBB0_495:
	v_cvt_pk_bf16_f32 v144, v144, v145
	s_nop 0
	v_cvt_pk_bf16_f32 v145, v146, v147
	global_store_dwordx2 v[142:143], v[144:145], off offset:32
	s_and_b64 vcc, exec, s[0:1]
	v_mov_b32_e32 v144, v110
	v_mov_b32_e32 v145, v111
	v_mov_b32_e32 v146, v112
	v_mov_b32_e32 v147, v113
	s_cbranch_vccnz .LBB0_497
	s_waitcnt vmcnt(29)
	v_lshlrev_b32_e32 v146, 16, v162
	v_and_b32_e32 v147, 0xffff0000, v162
	v_lshlrev_b32_e32 v148, 16, v163
	v_and_b32_e32 v149, 0xffff0000, v163
	v_add_u32_e32 v198, 0xb0, v136
	v_mad_i64_i32 v[198:199], s[2:3], v198, s93, 0
	v_lshl_add_u64 v[198:199], s[28:29], 0, v[198:199]
	v_lshl_add_u64 v[198:199], v[134:135], 1, v[198:199]
	global_load_dwordx2 v[162:163], v[198:199], off offset:256
	v_pk_fma_f32 v[144:145], v[146:147], s[30:31], v[110:111] op_sel_hi:[1,0,1]
	v_pk_fma_f32 v[146:147], v[148:149], s[30:31], v[112:113] op_sel_hi:[1,0,1]
.LBB0_497:
	v_cvt_pk_bf16_f32 v144, v144, v145
	s_nop 0
	v_cvt_pk_bf16_f32 v145, v146, v147
	global_store_dwordx2 v[142:143], v[144:145], off offset:256
	s_and_b64 vcc, exec, s[0:1]
	v_mov_b32_e32 v144, v106
	v_mov_b32_e32 v145, v107
	v_mov_b32_e32 v146, v108
	v_mov_b32_e32 v147, v109
	s_cbranch_vccnz .LBB0_499
	s_waitcnt vmcnt(30)
	v_lshlrev_b32_e32 v144, 16, v164
	v_and_b32_e32 v145, 0xffff0000, v164
	v_lshlrev_b32_e32 v140, 16, v165
	v_and_b32_e32 v141, 0xffff0000, v165
	v_add_u32_e32 v198, 0xb0, v136
	v_mad_i64_i32 v[198:199], s[2:3], v198, s93, 0
	v_lshl_add_u64 v[198:199], s[28:29], 0, v[198:199]
	v_lshl_add_u64 v[198:199], v[134:135], 1, v[198:199]
	global_load_dwordx2 v[164:165], v[198:199], off offset:288
	v_pk_fma_f32 v[144:145], v[144:145], s[30:31], v[106:107] op_sel_hi:[1,0,1]
	v_pk_fma_f32 v[146:147], v[140:141], s[30:31], v[108:109] op_sel_hi:[1,0,1]
.LBB0_499:
	v_cvt_pk_bf16_f32 v140, v144, v145
	s_nop 0
	v_cvt_pk_bf16_f32 v141, v146, v147
	global_store_dwordx2 v[142:143], v[140:141], off offset:288
	v_or_b32_e32 v142, 32, v136
	v_mad_i64_i32 v[140:141], s[2:3], v142, s93, 0
	s_and_b64 vcc, exec, s[0:1]
	v_mov_b32_e32 v144, v86
	v_mov_b32_e32 v145, v87
	v_mov_b32_e32 v146, v88
	v_mov_b32_e32 v147, v89
	s_cbranch_vccnz .LBB0_501
	s_waitcnt vmcnt(31)
	v_lshlrev_b32_e32 v146, 16, v166
	v_and_b32_e32 v147, 0xffff0000, v166
	v_lshlrev_b32_e32 v148, 16, v167
	v_and_b32_e32 v149, 0xffff0000, v167
	v_pk_fma_f32 v[144:145], v[146:147], s[30:31], v[86:87] op_sel_hi:[1,0,1]
	v_pk_fma_f32 v[146:147], v[148:149], s[30:31], v[88:89] op_sel_hi:[1,0,1]
.LBB0_501:
	v_ashrrev_i32_e32 v143, 31, v142
	v_lshlrev_b64 v[142:143], 12, v[142:143]
	v_lshl_add_u64 v[142:143], v[138:139], 0, v[142:143]
	v_cvt_pk_bf16_f32 v144, v144, v145
	v_cvt_pk_bf16_f32 v145, v146, v147
	global_store_dwordx2 v[142:143], v[144:145], off
	s_and_b64 vcc, exec, s[0:1]
	v_mov_b32_e32 v144, v82
	v_mov_b32_e32 v145, v83
	v_mov_b32_e32 v146, v84
	v_mov_b32_e32 v147, v85
	s_cbranch_vccnz .LBB0_503
	s_waitcnt vmcnt(31)
	v_lshlrev_b32_e32 v146, 16, v168
	v_and_b32_e32 v147, 0xffff0000, v168
	v_lshlrev_b32_e32 v148, 16, v169
	v_and_b32_e32 v149, 0xffff0000, v169
	v_pk_fma_f32 v[144:145], v[146:147], s[30:31], v[82:83] op_sel_hi:[1,0,1]
	v_pk_fma_f32 v[146:147], v[148:149], s[30:31], v[84:85] op_sel_hi:[1,0,1]
; __device__ __forceinline__ unsigned cvt_pk_bf16(float lo, float hi) { unsigned r; asm volatile("v_cvt_pk_bf16_f32 %0, %1, %2" : "=v"(r) : "v"(lo), "v"(hi)); return r; }
;     __device__ __forceinline__ void operator()(const f32x4 (&acc)[2][2][4][2], const Unit& u, int wr, int wc, int fr, int fq) const {
;     ...
;             for (int m = 0; m < 4; ++m) { const size_t off = (size_t)(row0 + ai * HALF + m * 16) * DM + col0, roff = (size_t)(row0 + ai * HALF + m * 16) * LDX + col0;
; #pragma unroll
;                 for (int bj = 0; bj < 2; ++bj)
; #pragma unroll
;                     for (int n = 0; n < 2; ++n) { f32x4 o = acc[ai][bj][m][n];
;                         if (addres) { const u32x2 w = *(const u32x2*)(res + roff + bj * HALF + n * 16);
;                             o[0] += ALPHA * __uint_as_float(w.x << 16); o[1] += ALPHA * __uint_as_float(w.x & 0xffff0000u); o[2] += ALPHA * __uint_as_float(w.y << 16); o[3] += ALPHA * __uint_as_float(w.y & 0xffff0000u); }
;                         u32x2 pk; pk.x = cvt_pk_bf16(o[0], o[1]); pk.y = cvt_pk_bf16(o[2], o[3]);
;                         *(u32x2*)(base + off + bj * HALF + n * 16) = pk; } }
.LBB0_503:
	v_cvt_pk_bf16_f32 v144, v144, v145
	s_nop 0
	v_cvt_pk_bf16_f32 v145, v146, v147
	global_store_dwordx2 v[142:143], v[144:145], off offset:32
	s_and_b64 vcc, exec, s[0:1]
	v_mov_b32_e32 v144, v94
	v_mov_b32_e32 v145, v95
	v_mov_b32_e32 v146, v96
	v_mov_b32_e32 v147, v97
	s_cbranch_vccnz .LBB0_505
	s_waitcnt vmcnt(31)
	v_lshlrev_b32_e32 v146, 16, v170
	v_and_b32_e32 v147, 0xffff0000, v170
	v_lshlrev_b32_e32 v148, 16, v171
	v_and_b32_e32 v149, 0xffff0000, v171
	v_pk_fma_f32 v[144:145], v[146:147], s[30:31], v[94:95] op_sel_hi:[1,0,1]
	v_pk_fma_f32 v[146:147], v[148:149], s[30:31], v[96:97] op_sel_hi:[1,0,1]
.LBB0_505:
	v_cvt_pk_bf16_f32 v144, v144, v145
	s_nop 0
	v_cvt_pk_bf16_f32 v145, v146, v147
	global_store_dwordx2 v[142:143], v[144:145], off offset:256
	s_and_b64 vcc, exec, s[0:1]
	v_mov_b32_e32 v144, v90
	v_mov_b32_e32 v145, v91
	v_mov_b32_e32 v146, v92
	v_mov_b32_e32 v147, v93
	s_cbranch_vccnz .LBB0_507
	s_waitcnt vmcnt(31)
	v_lshlrev_b32_e32 v144, 16, v172
	v_and_b32_e32 v145, 0xffff0000, v172
	v_lshlrev_b32_e32 v140, 16, v173
	v_and_b32_e32 v141, 0xffff0000, v173
	v_pk_fma_f32 v[144:145], v[144:145], s[30:31], v[90:91] op_sel_hi:[1,0,1]
	v_pk_fma_f32 v[146:147], v[140:141], s[30:31], v[92:93] op_sel_hi:[1,0,1]
.LBB0_507:
	v_cvt_pk_bf16_f32 v140, v144, v145
	s_nop 0
	v_cvt_pk_bf16_f32 v141, v146, v147
	global_store_dwordx2 v[142:143], v[140:141], off offset:288
	v_or_b32_e32 v142, 48, v136
	v_mad_i64_i32 v[140:141], s[2:3], v142, s93, 0
	s_and_b64 vcc, exec, s[0:1]
	v_mov_b32_e32 v144, v70
	v_mov_b32_e32 v145, v71
	v_mov_b32_e32 v146, v72
	v_mov_b32_e32 v147, v73
	s_cbranch_vccnz .LBB0_509
	s_waitcnt vmcnt(31)
	v_lshlrev_b32_e32 v146, 16, v174
	v_and_b32_e32 v147, 0xffff0000, v174
	v_lshlrev_b32_e32 v148, 16, v175
	v_and_b32_e32 v149, 0xffff0000, v175
	v_pk_fma_f32 v[144:145], v[146:147], s[30:31], v[70:71] op_sel_hi:[1,0,1]
	v_pk_fma_f32 v[146:147], v[148:149], s[30:31], v[72:73] op_sel_hi:[1,0,1]
.LBB0_509:
	v_ashrrev_i32_e32 v143, 31, v142
	v_lshlrev_b64 v[142:143], 12, v[142:143]
	v_lshl_add_u64 v[142:143], v[138:139], 0, v[142:143]
	v_cvt_pk_bf16_f32 v144, v144, v145
	v_cvt_pk_bf16_f32 v145, v146, v147
	global_store_dwordx2 v[142:143], v[144:145], off
	s_and_b64 vcc, exec, s[0:1]
	v_mov_b32_e32 v144, v66
	v_mov_b32_e32 v145, v67
	v_mov_b32_e32 v146, v68
	v_mov_b32_e32 v147, v69
	s_cbranch_vccnz .LBB0_511
	s_waitcnt vmcnt(31)
	v_lshlrev_b32_e32 v146, 16, v176
	v_and_b32_e32 v147, 0xffff0000, v176
	v_lshlrev_b32_e32 v148, 16, v177
	v_and_b32_e32 v149, 0xffff0000, v177
	v_pk_fma_f32 v[144:145], v[146:147], s[30:31], v[66:67] op_sel_hi:[1,0,1]
	v_pk_fma_f32 v[146:147], v[148:149], s[30:31], v[68:69] op_sel_hi:[1,0,1]
.LBB0_511:
	v_cvt_pk_bf16_f32 v144, v144, v145
	s_nop 0
	v_cvt_pk_bf16_f32 v145, v146, v147
	global_store_dwordx2 v[142:143], v[144:145], off offset:32
	s_and_b64 vcc, exec, s[0:1]
	v_mov_b32_e32 v144, v78
	v_mov_b32_e32 v145, v79
	v_mov_b32_e32 v146, v80
	v_mov_b32_e32 v147, v81
	s_cbranch_vccnz .LBB0_513
	s_waitcnt vmcnt(31)
	v_lshlrev_b32_e32 v146, 16, v178
	v_and_b32_e32 v147, 0xffff0000, v178
	v_lshlrev_b32_e32 v148, 16, v179
	v_and_b32_e32 v149, 0xffff0000, v179
	v_pk_fma_f32 v[144:145], v[146:147], s[30:31], v[78:79] op_sel_hi:[1,0,1]
	v_pk_fma_f32 v[146:147], v[148:149], s[30:31], v[80:81] op_sel_hi:[1,0,1]
.LBB0_513:
	v_cvt_pk_bf16_f32 v144, v144, v145
	s_nop 0
	v_cvt_pk_bf16_f32 v145, v146, v147
	global_store_dwordx2 v[142:143], v[144:145], off offset:256
	s_and_b64 vcc, exec, s[0:1]
	v_mov_b32_e32 v144, v74
	v_mov_b32_e32 v145, v75
	v_mov_b32_e32 v146, v76
	v_mov_b32_e32 v147, v77
	s_cbranch_vccnz .LBB0_515
	s_waitcnt vmcnt(31)
	v_lshlrev_b32_e32 v144, 16, v180
	v_and_b32_e32 v145, 0xffff0000, v180
	v_lshlrev_b32_e32 v140, 16, v181
	v_and_b32_e32 v141, 0xffff0000, v181
	v_pk_fma_f32 v[144:145], v[144:145], s[30:31], v[74:75] op_sel_hi:[1,0,1]
	v_pk_fma_f32 v[146:147], v[140:141], s[30:31], v[76:77] op_sel_hi:[1,0,1]
.LBB0_515:
	v_cvt_pk_bf16_f32 v140, v144, v145
	s_nop 0
	v_cvt_pk_bf16_f32 v141, v146, v147
	global_store_dwordx2 v[142:143], v[140:141], off offset:288
	v_add_u32_e32 v142, 0x80, v136
	v_mad_i64_i32 v[140:141], s[2:3], v142, s93, 0
	s_and_b64 vcc, exec, s[0:1]
	v_mov_b32_e32 v144, v52
	v_mov_b32_e32 v145, v53
	v_mov_b32_e32 v146, v54
	v_mov_b32_e32 v147, v55
	s_cbranch_vccnz .LBB0_517
	s_waitcnt vmcnt(31)
	v_lshlrev_b32_e32 v146, 16, v182
	v_and_b32_e32 v147, 0xffff0000, v182
	v_lshlrev_b32_e32 v148, 16, v183
	v_and_b32_e32 v149, 0xffff0000, v183
	v_pk_fma_f32 v[144:145], v[146:147], s[30:31], v[52:53] op_sel_hi:[1,0,1]
	v_pk_fma_f32 v[146:147], v[148:149], s[30:31], v[54:55] op_sel_hi:[1,0,1]
.LBB0_517:
	v_ashrrev_i32_e32 v143, 31, v142
	v_lshlrev_b64 v[142:143], 12, v[142:143]
	v_lshl_add_u64 v[142:143], v[138:139], 0, v[142:143]
	v_cvt_pk_bf16_f32 v144, v144, v145
	v_cvt_pk_bf16_f32 v145, v146, v147
	global_store_dwordx2 v[142:143], v[144:145], off
	s_and_b64 vcc, exec, s[0:1]
	v_mov_b32_e32 v144, v48
	v_mov_b32_e32 v145, v49
	v_mov_b32_e32 v146, v50
	v_mov_b32_e32 v147, v51
	s_cbranch_vccnz .LBB0_519
	s_waitcnt vmcnt(31)
	v_lshlrev_b32_e32 v146, 16, v184
	v_and_b32_e32 v147, 0xffff0000, v184
	v_lshlrev_b32_e32 v148, 16, v185
	v_and_b32_e32 v149, 0xffff0000, v185
	v_pk_fma_f32 v[144:145], v[146:147], s[30:31], v[48:49] op_sel_hi:[1,0,1]
	v_pk_fma_f32 v[146:147], v[148:149], s[30:31], v[50:51] op_sel_hi:[1,0,1]
; __device__ __forceinline__ unsigned cvt_pk_bf16(float lo, float hi) { unsigned r; asm volatile("v_cvt_pk_bf16_f32 %0, %1, %2" : "=v"(r) : "v"(lo), "v"(hi)); return r; }
;     __device__ __forceinline__ void operator()(const f32x4 (&acc)[2][2][4][2], const Unit& u, int wr, int wc, int fr, int fq) const {
;     ...
;             for (int m = 0; m < 4; ++m) { const size_t off = (size_t)(row0 + ai * HALF + m * 16) * DM + col0, roff = (size_t)(row0 + ai * HALF + m * 16) * LDX + col0;
; #pragma unroll
;                 for (int bj = 0; bj < 2; ++bj)
; #pragma unroll
;                     for (int n = 0; n < 2; ++n) { f32x4 o = acc[ai][bj][m][n];
;                         if (addres) { const u32x2 w = *(const u32x2*)(res + roff + bj * HALF + n * 16);
;                             o[0] += ALPHA * __uint_as_float(w.x << 16); o[1] += ALPHA * __uint_as_float(w.x & 0xffff0000u); o[2] += ALPHA * __uint_as_float(w.y << 16); o[3] += ALPHA * __uint_as_float(w.y & 0xffff0000u); }
;                         u32x2 pk; pk.x = cvt_pk_bf16(o[0], o[1]); pk.y = cvt_pk_bf16(o[2], o[3]);
;                         *(u32x2*)(base + off + bj * HALF + n * 16) = pk; } }
.LBB0_519:
	v_cvt_pk_bf16_f32 v144, v144, v145
	s_nop 0
	v_cvt_pk_bf16_f32 v145, v146, v147
	global_store_dwordx2 v[142:143], v[144:145], off offset:32
	s_and_b64 vcc, exec, s[0:1]
	v_mov_b32_e32 v144, v60
	v_mov_b32_e32 v145, v61
	v_mov_b32_e32 v146, v62
	v_mov_b32_e32 v147, v63
	s_cbranch_vccnz .LBB0_521
	s_waitcnt vmcnt(31)
	v_lshlrev_b32_e32 v146, 16, v186
	v_and_b32_e32 v147, 0xffff0000, v186
	v_lshlrev_b32_e32 v148, 16, v187
	v_and_b32_e32 v149, 0xffff0000, v187
	v_pk_fma_f32 v[144:145], v[146:147], s[30:31], v[60:61] op_sel_hi:[1,0,1]
	v_pk_fma_f32 v[146:147], v[148:149], s[30:31], v[62:63] op_sel_hi:[1,0,1]
.LBB0_521:
	v_cvt_pk_bf16_f32 v144, v144, v145
	s_nop 0
	v_cvt_pk_bf16_f32 v145, v146, v147
	global_store_dwordx2 v[142:143], v[144:145], off offset:256
	s_and_b64 vcc, exec, s[0:1]
	v_mov_b32_e32 v144, v56
	v_mov_b32_e32 v145, v57
	v_mov_b32_e32 v146, v58
	v_mov_b32_e32 v147, v59
	s_cbranch_vccnz .LBB0_523
	s_waitcnt vmcnt(31)
	v_lshlrev_b32_e32 v144, 16, v188
	v_and_b32_e32 v145, 0xffff0000, v188
	v_lshlrev_b32_e32 v140, 16, v189
	v_and_b32_e32 v141, 0xffff0000, v189
	v_pk_fma_f32 v[144:145], v[144:145], s[30:31], v[56:57] op_sel_hi:[1,0,1]
	v_pk_fma_f32 v[146:147], v[140:141], s[30:31], v[58:59] op_sel_hi:[1,0,1]
.LBB0_523:
	v_cvt_pk_bf16_f32 v140, v144, v145
	s_nop 0
	v_cvt_pk_bf16_f32 v141, v146, v147
	global_store_dwordx2 v[142:143], v[140:141], off offset:288
	v_add_u32_e32 v142, 0x90, v136
	v_mad_i64_i32 v[140:141], s[2:3], v142, s93, 0
	s_and_b64 vcc, exec, s[0:1]
	v_mov_b32_e32 v144, v36
	v_mov_b32_e32 v145, v37
	v_mov_b32_e32 v146, v38
	v_mov_b32_e32 v147, v39
	s_cbranch_vccnz .LBB0_525
	s_waitcnt vmcnt(31)
	v_lshlrev_b32_e32 v146, 16, v190
	v_and_b32_e32 v147, 0xffff0000, v190
	v_lshlrev_b32_e32 v148, 16, v191
	v_and_b32_e32 v149, 0xffff0000, v191
	v_pk_fma_f32 v[144:145], v[146:147], s[30:31], v[36:37] op_sel_hi:[1,0,1]
	v_pk_fma_f32 v[146:147], v[148:149], s[30:31], v[38:39] op_sel_hi:[1,0,1]
.LBB0_525:
	v_ashrrev_i32_e32 v143, 31, v142
	v_lshlrev_b64 v[142:143], 12, v[142:143]
	v_lshl_add_u64 v[142:143], v[138:139], 0, v[142:143]
	v_cvt_pk_bf16_f32 v144, v144, v145
	v_cvt_pk_bf16_f32 v145, v146, v147
	global_store_dwordx2 v[142:143], v[144:145], off
	s_and_b64 vcc, exec, s[0:1]
	v_mov_b32_e32 v144, v32
	v_mov_b32_e32 v145, v33
	v_mov_b32_e32 v146, v34
	v_mov_b32_e32 v147, v35
	s_cbranch_vccnz .LBB0_527
	s_waitcnt vmcnt(31)
	v_lshlrev_b32_e32 v146, 16, v192
	v_and_b32_e32 v147, 0xffff0000, v192
	v_lshlrev_b32_e32 v148, 16, v193
	v_and_b32_e32 v149, 0xffff0000, v193
	v_pk_fma_f32 v[144:145], v[146:147], s[30:31], v[32:33] op_sel_hi:[1,0,1]
	v_pk_fma_f32 v[146:147], v[148:149], s[30:31], v[34:35] op_sel_hi:[1,0,1]
.LBB0_527:
	v_cvt_pk_bf16_f32 v144, v144, v145
	s_nop 0
	v_cvt_pk_bf16_f32 v145, v146, v147
	global_store_dwordx2 v[142:143], v[144:145], off offset:32
	s_and_b64 vcc, exec, s[0:1]
	v_mov_b32_e32 v144, v44
	v_mov_b32_e32 v145, v45
	v_mov_b32_e32 v146, v46
	v_mov_b32_e32 v147, v47
	s_cbranch_vccnz .LBB0_529
	s_waitcnt vmcnt(31)
	v_lshlrev_b32_e32 v146, 16, v194
	v_and_b32_e32 v147, 0xffff0000, v194
	v_lshlrev_b32_e32 v148, 16, v195
	v_and_b32_e32 v149, 0xffff0000, v195
	v_pk_fma_f32 v[144:145], v[146:147], s[30:31], v[44:45] op_sel_hi:[1,0,1]
	v_pk_fma_f32 v[146:147], v[148:149], s[30:31], v[46:47] op_sel_hi:[1,0,1]
.LBB0_529:
	v_cvt_pk_bf16_f32 v144, v144, v145
	s_nop 0
	v_cvt_pk_bf16_f32 v145, v146, v147
	global_store_dwordx2 v[142:143], v[144:145], off offset:256
	s_and_b64 vcc, exec, s[0:1]
	v_mov_b32_e32 v144, v40
	v_mov_b32_e32 v145, v41
	v_mov_b32_e32 v146, v42
	v_mov_b32_e32 v147, v43
	s_cbranch_vccnz .LBB0_531
	s_waitcnt vmcnt(31)
	v_lshlrev_b32_e32 v144, 16, v196
	v_and_b32_e32 v145, 0xffff0000, v196
	v_lshlrev_b32_e32 v140, 16, v197
	v_and_b32_e32 v141, 0xffff0000, v197
	v_pk_fma_f32 v[144:145], v[144:145], s[30:31], v[40:41] op_sel_hi:[1,0,1]
	v_pk_fma_f32 v[146:147], v[140:141], s[30:31], v[42:43] op_sel_hi:[1,0,1]
.LBB0_531:
	v_cvt_pk_bf16_f32 v140, v144, v145
	s_nop 0
	v_cvt_pk_bf16_f32 v141, v146, v147
	global_store_dwordx2 v[142:143], v[140:141], off offset:288
	v_add_u32_e32 v142, 0xa0, v136
	v_mad_i64_i32 v[140:141], s[2:3], v142, s93, 0
	s_and_b64 vcc, exec, s[0:1]
	v_mov_b32_e32 v144, v20
	v_mov_b32_e32 v145, v21
	v_mov_b32_e32 v146, v22
	v_mov_b32_e32 v147, v23
	s_cbranch_vccnz .LBB0_533
	s_waitcnt vmcnt(31)
	v_lshlrev_b32_e32 v146, 16, v150
	v_and_b32_e32 v147, 0xffff0000, v150
	v_lshlrev_b32_e32 v148, 16, v151
	v_and_b32_e32 v149, 0xffff0000, v151
	v_pk_fma_f32 v[144:145], v[146:147], s[30:31], v[20:21] op_sel_hi:[1,0,1]
	v_pk_fma_f32 v[146:147], v[148:149], s[30:31], v[22:23] op_sel_hi:[1,0,1]
; __device__ __forceinline__ unsigned cvt_pk_bf16(float lo, float hi) { unsigned r; asm volatile("v_cvt_pk_bf16_f32 %0, %1, %2" : "=v"(r) : "v"(lo), "v"(hi)); return r; }
;     __device__ __forceinline__ void operator()(const f32x4 (&acc)[2][2][4][2], const Unit& u, int wr, int wc, int fr, int fq) const {
;     ...
;             for (int m = 0; m < 4; ++m) { const size_t off = (size_t)(row0 + ai * HALF + m * 16) * DM + col0, roff = (size_t)(row0 + ai * HALF + m * 16) * LDX + col0;
; #pragma unroll
;                 for (int bj = 0; bj < 2; ++bj)
; #pragma unroll
;                     for (int n = 0; n < 2; ++n) { f32x4 o = acc[ai][bj][m][n];
;                         if (addres) { const u32x2 w = *(const u32x2*)(res + roff + bj * HALF + n * 16);
;                             o[0] += ALPHA * __uint_as_float(w.x << 16); o[1] += ALPHA * __uint_as_float(w.x & 0xffff0000u); o[2] += ALPHA * __uint_as_float(w.y << 16); o[3] += ALPHA * __uint_as_float(w.y & 0xffff0000u); }
;                         u32x2 pk; pk.x = cvt_pk_bf16(o[0], o[1]); pk.y = cvt_pk_bf16(o[2], o[3]);
;                         *(u32x2*)(base + off + bj * HALF + n * 16) = pk; } }
.LBB0_533:
	v_ashrrev_i32_e32 v143, 31, v142
	v_lshlrev_b64 v[142:143], 12, v[142:143]
	v_lshl_add_u64 v[142:143], v[138:139], 0, v[142:143]
	v_cvt_pk_bf16_f32 v144, v144, v145
	v_cvt_pk_bf16_f32 v145, v146, v147
	global_store_dwordx2 v[142:143], v[144:145], off
	s_and_b64 vcc, exec, s[0:1]
	v_mov_b32_e32 v144, v16
	v_mov_b32_e32 v145, v17
	v_mov_b32_e32 v146, v18
	v_mov_b32_e32 v147, v19
	s_cbranch_vccnz .LBB0_535
	s_waitcnt vmcnt(30)
	v_lshlrev_b32_e32 v146, 16, v152
	v_and_b32_e32 v147, 0xffff0000, v152
	v_lshlrev_b32_e32 v148, 16, v153
	v_and_b32_e32 v149, 0xffff0000, v153
	v_pk_fma_f32 v[144:145], v[146:147], s[30:31], v[16:17] op_sel_hi:[1,0,1]
	v_pk_fma_f32 v[146:147], v[148:149], s[30:31], v[18:19] op_sel_hi:[1,0,1]
.LBB0_535:
	v_cvt_pk_bf16_f32 v144, v144, v145
	s_nop 0
	v_cvt_pk_bf16_f32 v145, v146, v147
	global_store_dwordx2 v[142:143], v[144:145], off offset:32
	s_and_b64 vcc, exec, s[0:1]
	v_mov_b32_e32 v144, v28
	v_mov_b32_e32 v145, v29
	v_mov_b32_e32 v146, v30
	v_mov_b32_e32 v147, v31
	s_cbranch_vccnz .LBB0_537
	s_waitcnt vmcnt(29)
	v_lshlrev_b32_e32 v146, 16, v154
	v_and_b32_e32 v147, 0xffff0000, v154
	v_lshlrev_b32_e32 v148, 16, v155
	v_and_b32_e32 v149, 0xffff0000, v155
	v_pk_fma_f32 v[144:145], v[146:147], s[30:31], v[28:29] op_sel_hi:[1,0,1]
	v_pk_fma_f32 v[146:147], v[148:149], s[30:31], v[30:31] op_sel_hi:[1,0,1]
.LBB0_537:
	v_cvt_pk_bf16_f32 v144, v144, v145
	s_nop 0
	v_cvt_pk_bf16_f32 v145, v146, v147
	global_store_dwordx2 v[142:143], v[144:145], off offset:256
	s_and_b64 vcc, exec, s[0:1]
	v_mov_b32_e32 v144, v24
	v_mov_b32_e32 v145, v25
	v_mov_b32_e32 v146, v26
	v_mov_b32_e32 v147, v27
	s_cbranch_vccnz .LBB0_539
	s_waitcnt vmcnt(28)
	v_lshlrev_b32_e32 v144, 16, v156
	v_and_b32_e32 v145, 0xffff0000, v156
	v_lshlrev_b32_e32 v140, 16, v157
	v_and_b32_e32 v141, 0xffff0000, v157
	v_pk_fma_f32 v[144:145], v[144:145], s[30:31], v[24:25] op_sel_hi:[1,0,1]
	v_pk_fma_f32 v[146:147], v[140:141], s[30:31], v[26:27] op_sel_hi:[1,0,1]
.LBB0_539:
	v_cvt_pk_bf16_f32 v140, v144, v145
	s_nop 0
	v_cvt_pk_bf16_f32 v141, v146, v147
	global_store_dwordx2 v[142:143], v[140:141], off offset:288
	v_add_u32_e32 v140, 0xb0, v136
	v_mad_i64_i32 v[136:137], s[2:3], v140, s93, 0
	s_and_b64 vcc, exec, s[0:1]
	v_mov_b32_e32 v142, v4
	v_mov_b32_e32 v143, v5
	v_mov_b32_e32 v144, v6
	v_mov_b32_e32 v145, v7
	s_cbranch_vccnz .LBB0_541
	s_waitcnt vmcnt(27)
	v_lshlrev_b32_e32 v144, 16, v158
	v_and_b32_e32 v145, 0xffff0000, v158
	v_lshlrev_b32_e32 v146, 16, v159
	v_and_b32_e32 v147, 0xffff0000, v159
	v_pk_fma_f32 v[142:143], v[144:145], s[30:31], v[4:5] op_sel_hi:[1,0,1]
	v_pk_fma_f32 v[144:145], v[146:147], s[30:31], v[6:7] op_sel_hi:[1,0,1]
.LBB0_541:
	v_ashrrev_i32_e32 v141, 31, v140
	v_lshlrev_b64 v[140:141], 12, v[140:141]
	v_lshl_add_u64 v[138:139], v[138:139], 0, v[140:141]
	v_cvt_pk_bf16_f32 v140, v142, v143
	v_cvt_pk_bf16_f32 v141, v144, v145
	global_store_dwordx2 v[138:139], v[140:141], off
	s_and_b64 vcc, exec, s[0:1]
	v_mov_b32_e32 v140, v0
	v_mov_b32_e32 v141, v1
	v_mov_b32_e32 v142, v2
	v_mov_b32_e32 v143, v3
	s_cbranch_vccnz .LBB0_543
	s_waitcnt vmcnt(26)
	v_lshlrev_b32_e32 v142, 16, v160
	v_and_b32_e32 v143, 0xffff0000, v160
	v_lshlrev_b32_e32 v144, 16, v161
	v_and_b32_e32 v145, 0xffff0000, v161
	v_pk_fma_f32 v[140:141], v[142:143], s[30:31], v[0:1] op_sel_hi:[1,0,1]
	v_pk_fma_f32 v[142:143], v[144:145], s[30:31], v[2:3] op_sel_hi:[1,0,1]
.LBB0_543:
	v_cvt_pk_bf16_f32 v140, v140, v141
	s_nop 0
	v_cvt_pk_bf16_f32 v141, v142, v143
	global_store_dwordx2 v[138:139], v[140:141], off offset:32
	s_and_b64 vcc, exec, s[0:1]
	v_mov_b32_e32 v140, v12
	v_mov_b32_e32 v141, v13
	v_mov_b32_e32 v142, v14
	v_mov_b32_e32 v143, v15
	s_cbranch_vccnz .LBB0_545
	s_waitcnt vmcnt(25)
	v_lshlrev_b32_e32 v142, 16, v162
	v_and_b32_e32 v143, 0xffff0000, v162
	v_lshlrev_b32_e32 v144, 16, v163
	v_and_b32_e32 v145, 0xffff0000, v163
	v_pk_fma_f32 v[140:141], v[142:143], s[30:31], v[12:13] op_sel_hi:[1,0,1]
	v_pk_fma_f32 v[142:143], v[144:145], s[30:31], v[14:15] op_sel_hi:[1,0,1]
.LBB0_545:
	v_cvt_pk_bf16_f32 v140, v140, v141
	s_nop 0
	v_cvt_pk_bf16_f32 v141, v142, v143
	global_store_dwordx2 v[138:139], v[140:141], off offset:256
	s_and_b64 vcc, exec, s[0:1]
	v_mov_b32_e32 v140, v8
	v_mov_b32_e32 v141, v9
	v_mov_b32_e32 v142, v10
	v_mov_b32_e32 v143, v11
	s_cbranch_vccnz .LBB0_547
	s_waitcnt vmcnt(24)
	v_lshlrev_b32_e32 v140, 16, v164
	v_and_b32_e32 v141, 0xffff0000, v164
	v_lshlrev_b32_e32 v136, 16, v165
	v_and_b32_e32 v137, 0xffff0000, v165
	v_pk_fma_f32 v[140:141], v[140:141], s[30:31], v[8:9] op_sel_hi:[1,0,1]
	v_pk_fma_f32 v[142:143], v[136:137], s[30:31], v[10:11] op_sel_hi:[1,0,1]
